# H1: the 16 f32->bf16 RNE bit-trick conversions (bfe/add3/lshr/and_or, 48 instrs) replaced by 8 v_cvt_pk_bf16_f32 (same RNE rounding, as used everywhere else in the baseline); on top of v066
# speedup vs baseline: 1.0106x; 1.0048x over previous
; #define LAS __attribute__((address_space(3)))
; __device__ __forceinline__ unsigned f2bf(float f) { unsigned u = __builtin_bit_cast(unsigned, f); return (u + 0x7fffu + ((u >> 16) & 1u)) >> 16; }
; __device__ __forceinline__ bf16x8 mk_bf16x8(const float (&v)[8]) {
;     u32x4 w; w.x = f2bf(v[0]) | (f2bf(v[1]) << 16); w.y = f2bf(v[2]) | (f2bf(v[3]) << 16); w.z = f2bf(v[4]) | (f2bf(v[5]) << 16); w.w = f2bf(v[6]) | (f2bf(v[7]) << 16);
;     return __builtin_bit_cast(bf16x8, w);
; }
; __device__ __forceinline__ void h1_phase(const Ptrs& P, LAS unsigned char* lds, int bx, int G, int tid) {
;     ...
;         float v0[8], v1[8];
; #pragma unroll
;         for (int u = 0; u < 8; ++u) { v0[u] = kk[u] * base * __builtin_amdgcn_rcpf(pc[u]); v1[u] = kk[8 + u] * base * __builtin_amdgcn_rcpf(pc[8 + u]); }
;         *(LAS bf16x8*)(KT + d * 72 + 16 * i) = mk_bf16x8(v0);
;         *(LAS bf16x8*)(KT + d * 72 + 16 * i + 8) = mk_bf16x8(v1);
;         if (i == 0) P.Dn[(size_t)it * HD + d] = base;
.LBB0_227:
	v_rcp_f32_e32 v68, v51
	v_rcp_f32_e32 v69, v52
	v_rcp_f32_e32 v70, v55
	v_rcp_f32_e32 v71, v56
	v_rcp_f32_e32 v50, v50
	v_rcp_f32_e32 v51, v9
	v_rcp_f32_e32 v52, v53
	v_rcp_f32_e32 v53, v54
	v_pk_mul_f32 v[0:1], v[0:1], v[8:9] op_sel_hi:[1,0]
	v_pk_mul_f32 v[6:7], v[6:7], v[8:9] op_sel_hi:[1,0]
	v_pk_mul_f32 v[2:3], v[2:3], v[8:9] op_sel_hi:[1,0]
	v_pk_mul_f32 v[4:5], v[4:5], v[8:9] op_sel_hi:[1,0]
	v_pk_mul_f32 v[0:1], v[68:69], v[0:1]
	v_pk_mul_f32 v[6:7], v[70:71], v[6:7]
	v_pk_mul_f32 v[12:13], v[12:13], v[8:9] op_sel_hi:[1,0]
	v_pk_mul_f32 v[10:11], v[10:11], v[8:9] op_sel_hi:[1,0]
	v_pk_mul_f32 v[14:15], v[14:15], v[8:9] op_sel_hi:[1,0]
	v_pk_mul_f32 v[32:33], v[32:33], v[8:9] op_sel_hi:[1,0]
	v_pk_mul_f32 v[2:3], v[50:51], v[2:3]
	v_pk_mul_f32 v[4:5], v[52:53], v[4:5]
	v_rcp_f32_e32 v58, v58
	v_rcp_f32_e32 v67, v59
	v_rcp_f32_e32 v59, v60
	v_rcp_f32_e32 v60, v61
	v_rcp_f32_e32 v62, v62
	v_rcp_f32_e32 v61, v63
	v_rcp_f32_e32 v63, v64
	v_rcp_f32_e32 v66, v57
	v_cvt_pk_bf16_f32 v0, v2, v0
	v_cvt_pk_bf16_f32 v1, v3, v1
	v_cvt_pk_bf16_f32 v2, v4, v6
	v_cvt_pk_bf16_f32 v3, v5, v7
	ds_write_b128 v47, v[0:3]
	v_pk_mul_f32 v[2:3], v[58:59], v[10:11]
	v_pk_mul_f32 v[6:7], v[62:63], v[32:33]
	v_pk_mul_f32 v[0:1], v[66:67], v[12:13]
	v_pk_mul_f32 v[4:5], v[60:61], v[14:15]
	v_cvt_pk_bf16_f32 v0, v0, v2
	v_cvt_pk_bf16_f32 v1, v1, v3
	v_cvt_pk_bf16_f32 v2, v4, v6
	v_cvt_pk_bf16_f32 v3, v5, v7
	s_andn2_b64 vcc, exec, s[16:17]
	ds_write_b128 v47, v[0:3] offset:16
	s_cbranch_vccnz .LBB0_229
	global_store_dword v[30:31], v8, off sc1
